# v080 + phase-0 weight conversion bf16 stores write-through (sc1)
# speedup vs baseline: 1.0017x; 1.0017x over previous
.LBB0_105:
	s_or_b64 s[6:7], s[6:7], s[8:9]
	s_andn2_b64 vcc, exec, s[6:7]
	s_cbranch_vccnz .LBB0_102
	s_andn2_b64 vcc, exec, s[0:1]
	s_mov_b64 s[0:1], -1
	s_cbranch_vccnz .LBB0_178
	s_mul_hi_i32 s0, s2, 0x58345f19
	v_mov_b32_e32 v2, s53
	s_lshr_b32 s1, s0, 31
	s_ashr_i32 s0, s0, 11
	ds_read_b64 v[2:3], v2
	s_add_i32 s8, s0, s1
	s_mul_i32 s88, s8, 0xffffe8c8
	s_add_i32 s88, s88, s2
	s_mul_i32 s1, s8, 0x480000
	s_mul_hi_i32 s0, s8, 0x480000
	s_add_u32 s46, s29, s1
	s_addc_u32 s47, s31, s0
	s_waitcnt lgkmcnt(0)
	v_readfirstlane_b32 s0, v2
	s_mul_i32 s6, s8, 0x6c0000
	v_readfirstlane_b32 s1, v3
	s_mul_hi_i32 s7, s8, 0x6c0000
	s_add_u32 s6, s0, s6
	s_addc_u32 s7, s1, s7
	s_cmpk_gt_i32 s88, 0x15f
	s_mov_b64 s[0:1], -1
	s_cbranch_scc0 .LBB0_175
	s_cmpk_gt_u32 s88, 0x2df
	s_cbranch_scc0 .LBB0_172
	s_cmpk_gt_u32 s88, 0x35f
	s_cbranch_scc0 .LBB0_169
	s_cmpk_gt_u32 s88, 0x367
	s_cbranch_scc0 .LBB0_166
	s_ashr_i32 s9, s8, 31
	s_cmpk_gt_u32 s88, 0x3a7
	s_cbranch_scc0 .LBB0_162
	s_cmpk_gt_u32 s88, 0x437
	s_cbranch_scc0 .LBB0_148
	s_cmpk_gt_u32 s88, 0x4b7
	s_cbranch_scc0 .LBB0_134
	s_cmpk_gt_u32 s88, 0x6b7
	s_cbranch_scc0 .LBB0_120
	s_cmpk_gt_u32 s88, 0x11b7
	s_mul_hi_i32 s10, s8, 0xb00000
	s_mul_i32 s11, s8, 0xb00000
	s_cbranch_scc0 .LBB0_117
	v_mov_b32_e32 v2, s54
	ds_read_b64 v[2:3], v2
	s_add_i32 s0, s88, 0xffffee48
	s_mul_i32 s19, s8, 0x580000
	s_mov_b32 s92, s91
	v_mov_b32_e32 v63, v39
	s_waitcnt lgkmcnt(0)
	v_readfirstlane_b32 s1, v2
	v_readfirstlane_b32 s16, v3
	s_add_u32 s1, s1, s11
	s_addc_u32 s16, s16, s10
	s_lshl_b32 s18, s0, 1
	s_lshl_b32 s0, s0, 5
	s_and_b32 s89, s18, 0x7fffffc0
	s_and_b32 s0, s0, 0x3e0
	s_mul_hi_i32 s18, s8, 0x580000
	s_add_u32 s90, s35, s19
	s_addc_u32 s91, s37, s18
	s_lshl_b32 s18, s0, 2
	v_or_b32_e32 v38, s89, v35
	s_add_u32 s18, s1, s18
	s_addc_u32 s19, s16, 0
	v_or_b32_e32 v4, 8, v38
	v_mov_b32_e32 v5, v39
	v_or_b32_e32 v10, 16, v38
	v_mov_b32_e32 v11, v39
	v_or_b32_e32 v12, 24, v38
	v_mov_b32_e32 v13, v39
	v_or_b32_e32 v18, 32, v38
	v_mov_b32_e32 v19, v39
	v_or_b32_e32 v20, 40, v38
	v_mov_b32_e32 v21, v39
	v_lshl_add_u64 v[30:31], s[18:19], 0, v[62:63]
	v_lshlrev_b64 v[2:3], 12, v[38:39]
	v_lshlrev_b64 v[4:5], 12, v[4:5]
	v_lshlrev_b64 v[10:11], 12, v[10:11]
	v_lshlrev_b64 v[12:13], 12, v[12:13]
	v_lshlrev_b64 v[18:19], 12, v[18:19]
	v_lshlrev_b64 v[20:21], 12, v[20:21]
	v_lshl_add_u64 v[2:3], v[30:31], 0, v[2:3]
	v_lshl_add_u64 v[6:7], v[30:31], 0, v[4:5]
	v_lshl_add_u64 v[10:11], v[30:31], 0, v[10:11]
	v_lshl_add_u64 v[14:15], v[30:31], 0, v[12:13]
	v_lshl_add_u64 v[18:19], v[30:31], 0, v[18:19]
	v_lshl_add_u64 v[22:23], v[30:31], 0, v[20:21]
	global_load_dwordx4 v[2:5], v[2:3], off nt
	s_nop 0
	global_load_dwordx4 v[6:9], v[6:7], off nt
	s_nop 0
	global_load_dwordx4 v[10:13], v[10:11], off nt
	s_nop 0
	global_load_dwordx4 v[14:17], v[14:15], off nt
	s_nop 0
	global_load_dwordx4 v[18:21], v[18:19], off nt
	s_nop 0
	global_load_dwordx4 v[22:25], v[22:23], off nt
	v_or_b32_e32 v26, 48, v38
	v_mov_b32_e32 v27, v39
	v_lshlrev_b64 v[26:27], 12, v[26:27]
	v_lshl_add_u64 v[26:27], v[30:31], 0, v[26:27]
	v_or_b32_e32 v38, 56, v38
	global_load_dwordx4 v[26:29], v[26:27], off nt
	v_lshlrev_b64 v[32:33], 12, v[38:39]
	v_lshl_add_u64 v[30:31], v[30:31], 0, v[32:33]
	global_load_dwordx4 v[30:33], v[30:31], off nt
	v_add_u32_e32 v63, v43, v57
	v_add_u32_e32 v64, 0x420, v63
	v_add_u32_e32 v65, 0x428, v63
	v_add_u32_e32 v66, 0x840, v63
	v_add_u32_e32 v68, 0x848, v63
	v_add_u32_e32 v82, 0xc60, v63
	v_add_u32_e32 v83, 0xc68, v63
	v_add_u32_e32 v84, 0x1080, v63
	v_add_u32_e32 v85, 0x1088, v63
	v_add_u32_e32 v86, 0x14a0, v63
	v_add_u32_e32 v87, 0x14a8, v63
	v_add_u32_e32 v88, 0x18c0, v63
	v_add_u32_e32 v89, 0x18c8, v63
	v_add_u32_e32 v90, 0x1ce0, v63
	v_add_u32_e32 v91, 0x1ce8, v63
	s_lshl_b32 s1, s89, 1
	s_add_u32 s18, s90, s1
	v_lshlrev_b32_e32 v38, 1, v42
	s_addc_u32 s19, s91, 0
	s_mov_b32 s91, s92
	s_waitcnt vmcnt(7)
	ds_write2_b32 v63, v2, v3 offset1:1
	ds_write2_b32 v63, v4, v5 offset0:2 offset1:3
	s_waitcnt vmcnt(6)
	ds_write2_b32 v64, v6, v7 offset1:1
	ds_write2_b32 v65, v8, v9 offset1:1
	s_waitcnt vmcnt(5)
	ds_write2_b32 v66, v10, v11 offset1:1
	ds_write2_b32 v68, v12, v13 offset1:1
	s_waitcnt vmcnt(4)
	ds_write2_b32 v82, v14, v15 offset1:1
	ds_write2_b32 v83, v16, v17 offset1:1
	s_waitcnt vmcnt(3)
	ds_write2_b32 v84, v18, v19 offset1:1
	ds_write2_b32 v85, v20, v21 offset1:1
	s_waitcnt vmcnt(2)
	ds_write2_b32 v86, v22, v23 offset1:1
	ds_write2_b32 v87, v24, v25 offset1:1
	s_waitcnt vmcnt(1)
	ds_write2_b32 v88, v26, v27 offset1:1
	ds_write2_b32 v89, v28, v29 offset1:1
	s_waitcnt vmcnt(0)
	ds_write2_b32 v90, v30, v31 offset1:1
	ds_write2_b32 v91, v32, v33 offset1:1
	s_waitcnt lgkmcnt(0)
	ds_read2_b32 v[6:7], v70 offset0:33 offset1:41
	ds_read2_b32 v[8:9], v70 offset1:8
	ds_read2_b32 v[10:11], v70 offset0:66 offset1:74
	ds_read2_b32 v[12:13], v70 offset0:99 offset1:107
	ds_read2_b32 v[14:15], v70 offset0:132 offset1:140
	ds_read2_b32 v[16:17], v70 offset0:165 offset1:173
	ds_read2_b32 v[18:19], v70 offset0:198 offset1:206
	ds_read2_b32 v[20:21], v70 offset0:231 offset1:239
	s_waitcnt lgkmcnt(6)
	v_cvt_pk_bf16_f32 v2, v8, v6
	v_or_b32_e32 v6, s0, v35
	v_lshl_add_u64 v[22:23], s[18:19], 0, v[38:39]
	v_mul_u32_u24_e32 v38, 0x1600, v6
	s_waitcnt lgkmcnt(4)
	v_cvt_pk_bf16_f32 v3, v10, v12
	s_waitcnt lgkmcnt(2)
	v_cvt_pk_bf16_f32 v4, v14, v16
	s_waitcnt lgkmcnt(0)
	v_cvt_pk_bf16_f32 v5, v18, v20
	v_lshl_add_u64 v[24:25], v[22:23], 0, v[38:39]
	global_store_dwordx4 v[24:25], v[2:5], off sc1
	v_or_b32_e32 v6, s0, v59
	v_mul_u32_u24_e32 v38, 0x1600, v6
	v_cvt_pk_bf16_f32 v2, v9, v7
	v_cvt_pk_bf16_f32 v3, v11, v13
	v_cvt_pk_bf16_f32 v4, v15, v17
	v_cvt_pk_bf16_f32 v5, v19, v21
	ds_read2_b32 v[8:9], v70 offset0:16 offset1:24
	ds_read2_b32 v[10:11], v70 offset0:49 offset1:57
	ds_read2_b32 v[12:13], v70 offset0:82 offset1:90
	ds_read2_b32 v[14:15], v70 offset0:115 offset1:123
	ds_read2_b32 v[16:17], v70 offset0:148 offset1:156
	ds_read2_b32 v[18:19], v70 offset0:181 offset1:189
	ds_read2_b32 v[20:21], v70 offset0:214 offset1:222
	ds_read2_b32 v[24:25], v70 offset0:247 offset1:255
	v_lshl_add_u64 v[6:7], v[22:23], 0, v[38:39]
	global_store_dwordx4 v[6:7], v[2:5], off sc1
	v_or_b32_e32 v6, s0, v67
	v_mul_u32_u24_e32 v38, 0x1600, v6
	s_waitcnt lgkmcnt(6)
	v_cvt_pk_bf16_f32 v2, v8, v10
	s_waitcnt lgkmcnt(4)
	v_cvt_pk_bf16_f32 v3, v12, v14
	s_waitcnt lgkmcnt(2)
	v_cvt_pk_bf16_f32 v4, v16, v18
	s_waitcnt lgkmcnt(0)
	v_cvt_pk_bf16_f32 v5, v20, v24
	v_lshl_add_u64 v[6:7], v[22:23], 0, v[38:39]
	global_store_dwordx4 v[6:7], v[2:5], off sc1
	v_or_b32_e32 v6, s0, v69
	v_mul_u32_u24_e32 v38, 0x1600, v6
	v_cvt_pk_bf16_f32 v2, v9, v11
	v_cvt_pk_bf16_f32 v3, v13, v15
	v_cvt_pk_bf16_f32 v4, v17, v19
	v_cvt_pk_bf16_f32 v5, v21, v25
	v_lshl_add_u64 v[6:7], v[22:23], 0, v[38:39]
	global_store_dwordx4 v[6:7], v[2:5], off sc1
	s_waitcnt lgkmcnt(0)
	s_mov_b64 s[0:1], 0
.LBB0_117:
	s_andn2_b64 vcc, exec, s[0:1]
	s_cbranch_vccnz .LBB0_119
	s_add_i32 s0, s88, 0xf948
	v_mov_b32_e32 v2, s55
	s_and_b32 s1, s0, 0xffff
	ds_read_b64 v[2:3], v2
	s_mul_i32 s1, s1, 0xba2f
	s_lshr_b32 s16, s1, 23
	s_mul_i32 s1, s16, 0xb0
	s_sub_i32 s0, s0, s1
	s_and_b32 s1, s0, 0xffff
	s_waitcnt lgkmcnt(0)
	v_readfirstlane_b32 s18, v2
	s_mul_i32 s90, s8, 0x1600000
	v_readfirstlane_b32 s19, v3
	s_mul_hi_i32 s89, s8, 0x1600000
	s_add_u32 s18, s18, s90
	s_addc_u32 s19, s19, s89
	s_bfe_i32 s0, s0, 0x10002
	s_lshl_b32 s89, s1, 4
	s_and_b32 s0, s0, 0xb00
	s_and_b32 s89, s89, 0xf80
	s_add_i32 s0, s0, s89
	s_lshl_b32 s89, s1, 5
	s_and_b32 s1, s89, 0x60
	s_or_b32 s0, s0, s1
	s_add_u32 s11, s39, s11
	s_addc_u32 s10, s41, s10
	s_lshl_b32 s0, s0, 2
	s_add_u32 s0, s18, s0
	v_lshl_or_b32 v4, s16, 6, v35
	s_addc_u32 s1, s19, 0
	v_mov_b32_e32 v63, v39
	v_lshl_add_u64 v[2:3], s[0:1], 0, v[62:63]
	v_mul_u32_u24_e32 v38, 0x5800, v4
	v_lshl_add_u64 v[30:31], v[2:3], 0, v[38:39]
	v_add_co_u32_e32 v6, vcc, s56, v30
	v_add_u32_e32 v38, v43, v57
	s_nop 0
	v_addc_co_u32_e32 v7, vcc, 0, v31, vcc
	v_add_co_u32_e32 v10, vcc, s57, v30
	global_load_dwordx4 v[2:5], v[30:31], off nt
	s_nop 0
	global_load_dwordx4 v[6:9], v[6:7], off nt
	v_addc_co_u32_e32 v11, vcc, 0, v31, vcc
	v_add_co_u32_e32 v14, vcc, s58, v30
	v_add_u32_e32 v63, 0x420, v38
	s_nop 0
	v_addc_co_u32_e32 v15, vcc, 0, v31, vcc
	v_add_co_u32_e32 v18, vcc, s59, v30
	global_load_dwordx4 v[10:13], v[10:11], off nt
	s_nop 0
	global_load_dwordx4 v[14:17], v[14:15], off nt
	v_addc_co_u32_e32 v19, vcc, 0, v31, vcc
	v_add_co_u32_e32 v22, vcc, s60, v30
	v_add_u32_e32 v64, 0x428, v38
	s_nop 0
	v_addc_co_u32_e32 v23, vcc, 0, v31, vcc
	global_load_dwordx4 v[18:21], v[18:19], off nt
	s_nop 0
	global_load_dwordx4 v[22:25], v[22:23], off nt
	v_add_co_u32_e32 v26, vcc, s61, v30
	v_add_u32_e32 v65, 0x840, v38
	s_nop 0
	v_addc_co_u32_e32 v27, vcc, 0, v31, vcc
	global_load_dwordx4 v[26:29], v[26:27], off nt
	v_add_co_u32_e32 v30, vcc, s62, v30
	v_add_u32_e32 v66, 0x848, v38
	s_nop 0
	v_addc_co_u32_e32 v31, vcc, 0, v31, vcc
	global_load_dwordx4 v[30:33], v[30:31], off nt
	v_add_u32_e32 v68, 0xc60, v38
	v_add_u32_e32 v82, 0xc68, v38
	v_add_u32_e32 v83, 0x1080, v38
	v_add_u32_e32 v84, 0x1088, v38
	v_add_u32_e32 v85, 0x14a0, v38
	v_add_u32_e32 v86, 0x14a8, v38
	v_add_u32_e32 v87, 0x18c0, v38
	v_add_u32_e32 v88, 0x18c8, v38
	v_add_u32_e32 v89, 0x1ce0, v38
	v_add_u32_e32 v90, 0x1ce8, v38
	s_lshl_b32 s0, s16, 7
	s_add_u32 s0, s11, s0
	s_addc_u32 s1, s10, 0
	s_waitcnt vmcnt(7)
	ds_write2_b32 v38, v2, v3 offset1:1
	ds_write2_b32 v38, v4, v5 offset0:2 offset1:3
	s_waitcnt vmcnt(6)
	ds_write2_b32 v63, v6, v7 offset1:1
	ds_write2_b32 v64, v8, v9 offset1:1
	s_waitcnt vmcnt(5)
	ds_write2_b32 v65, v10, v11 offset1:1
	ds_write2_b32 v66, v12, v13 offset1:1
	s_waitcnt vmcnt(4)
	ds_write2_b32 v68, v14, v15 offset1:1
	ds_write2_b32 v82, v16, v17 offset1:1
	s_waitcnt vmcnt(3)
	ds_write2_b32 v83, v18, v19 offset1:1
	ds_write2_b32 v84, v20, v21 offset1:1
	s_waitcnt vmcnt(2)
	ds_write2_b32 v85, v22, v23 offset1:1
	ds_write2_b32 v86, v24, v25 offset1:1
	s_waitcnt vmcnt(1)
	ds_write2_b32 v87, v26, v27 offset1:1
	ds_write2_b32 v88, v28, v29 offset1:1
	s_waitcnt vmcnt(0)
	ds_write2_b32 v89, v30, v31 offset1:1
	ds_write2_b32 v90, v32, v33 offset1:1
	s_waitcnt lgkmcnt(0)
	ds_read2_b32 v[6:7], v70 offset0:33 offset1:41
	ds_read2_b32 v[8:9], v70 offset1:8
	ds_read2_b32 v[10:11], v70 offset0:66 offset1:74
	ds_read2_b32 v[12:13], v70 offset0:99 offset1:107
	ds_read2_b32 v[14:15], v70 offset0:132 offset1:140
	ds_read2_b32 v[16:17], v70 offset0:165 offset1:173
	ds_read2_b32 v[18:19], v70 offset0:198 offset1:206
	ds_read2_b32 v[20:21], v70 offset0:231 offset1:239
	v_lshlrev_b32_e32 v38, 1, v42
	s_waitcnt lgkmcnt(6)
	v_cvt_pk_bf16_f32 v2, v8, v6
	v_or_b32_e32 v6, s89, v35
	v_lshl_add_u64 v[22:23], s[0:1], 0, v[38:39]
	v_lshlrev_b32_e32 v38, 11, v6
	s_waitcnt lgkmcnt(4)
	v_cvt_pk_bf16_f32 v3, v10, v12
	s_waitcnt lgkmcnt(2)
	v_cvt_pk_bf16_f32 v4, v14, v16
	s_waitcnt lgkmcnt(0)
	v_cvt_pk_bf16_f32 v5, v18, v20
	v_lshl_add_u64 v[24:25], v[22:23], 0, v[38:39]
	global_store_dwordx4 v[24:25], v[2:5], off sc1
	v_or_b32_e32 v6, s89, v59
	v_lshlrev_b32_e32 v38, 11, v6
	v_cvt_pk_bf16_f32 v2, v9, v7
	v_cvt_pk_bf16_f32 v3, v11, v13
	v_cvt_pk_bf16_f32 v4, v15, v17
	v_cvt_pk_bf16_f32 v5, v19, v21
	ds_read2_b32 v[8:9], v70 offset0:49 offset1:57
	ds_read2_b32 v[10:11], v70 offset0:16 offset1:24
	ds_read2_b32 v[12:13], v70 offset0:82 offset1:90
	ds_read2_b32 v[14:15], v70 offset0:115 offset1:123
	ds_read2_b32 v[16:17], v70 offset0:148 offset1:156
	ds_read2_b32 v[18:19], v70 offset0:181 offset1:189
	ds_read2_b32 v[20:21], v70 offset0:214 offset1:222
	ds_read2_b32 v[24:25], v70 offset0:247 offset1:255
	v_lshl_add_u64 v[6:7], v[22:23], 0, v[38:39]
	global_store_dwordx4 v[6:7], v[2:5], off sc1
	v_or_b32_e32 v6, s89, v67
	v_lshlrev_b32_e32 v38, 11, v6
	s_waitcnt lgkmcnt(6)
	v_cvt_pk_bf16_f32 v2, v10, v8
	s_waitcnt lgkmcnt(4)
	v_cvt_pk_bf16_f32 v3, v12, v14
	s_waitcnt lgkmcnt(2)
	v_cvt_pk_bf16_f32 v4, v16, v18
	s_waitcnt lgkmcnt(0)
	v_cvt_pk_bf16_f32 v5, v20, v24
	v_lshl_add_u64 v[6:7], v[22:23], 0, v[38:39]
	global_store_dwordx4 v[6:7], v[2:5], off sc1
	v_or_b32_e32 v6, s89, v69
	v_lshlrev_b32_e32 v38, 11, v6
	v_cvt_pk_bf16_f32 v2, v11, v9
	v_cvt_pk_bf16_f32 v3, v13, v15
	v_cvt_pk_bf16_f32 v4, v17, v19
	v_cvt_pk_bf16_f32 v5, v21, v25
	v_lshl_add_u64 v[6:7], v[22:23], 0, v[38:39]
	global_store_dwordx4 v[6:7], v[2:5], off sc1
	s_waitcnt lgkmcnt(0)

.LBB0_132:
	v_add_u32_e32 v11, 0x840, v19
	ds_write2_b32 v11, v6, v7 offset1:1
	v_add_u32_e32 v6, 0x848, v19
	ds_write2_b32 v6, v8, v9 offset1:1
	s_waitcnt vmcnt(0)
	v_pk_mul_f32 v[2:3], v[2:3], v[10:11] op_sel_hi:[1,0]
	v_add_u32_e32 v6, 0xc60, v19
	ds_write2_b32 v6, v2, v3 offset1:1
	v_pk_mul_f32 v[2:3], v[4:5], v[10:11] op_sel_hi:[1,0]
	v_add_u32_e32 v4, 0xc68, v19
	ds_write2_b32 v4, v2, v3 offset1:1
	s_waitcnt lgkmcnt(0)
	s_lshl_b64 s[0:1], s[8:9], 21
	s_add_u32 s0, s43, s0
	ds_read2_b32 v[6:7], v70 offset0:33 offset1:41
	ds_read2_b32 v[8:9], v70 offset1:8
	ds_read2_b32 v[10:11], v70 offset0:66 offset1:74
	ds_read2_b32 v[12:13], v70 offset0:99 offset1:107
	ds_read2_b32 v[14:15], v70 offset0:132 offset1:140
	ds_read2_b32 v[16:17], v70 offset0:165 offset1:173
	ds_read2_b32 v[18:19], v70 offset0:198 offset1:206
	ds_read2_b32 v[20:21], v70 offset0:231 offset1:239
	s_addc_u32 s1, s45, s1
	s_lshl_b32 s10, s89, 1
	s_add_u32 s0, s0, s10
	s_addc_u32 s1, s1, 0
	v_lshlrev_b32_e32 v38, 1, v42
	s_waitcnt lgkmcnt(6)
	v_cvt_pk_bf16_f32 v2, v8, v6
	v_or_b32_e32 v6, s16, v35
	v_lshl_add_u64 v[22:23], s[0:1], 0, v[38:39]
	v_lshlrev_b32_e32 v38, 11, v6
	s_waitcnt lgkmcnt(4)
	v_cvt_pk_bf16_f32 v3, v10, v12
	s_waitcnt lgkmcnt(2)
	v_cvt_pk_bf16_f32 v4, v14, v16
	s_waitcnt lgkmcnt(0)
	v_cvt_pk_bf16_f32 v5, v18, v20
	v_lshl_add_u64 v[24:25], v[22:23], 0, v[38:39]
	global_store_dwordx4 v[24:25], v[2:5], off sc1
	v_or_b32_e32 v6, s16, v59
	v_lshlrev_b32_e32 v38, 11, v6
	v_cvt_pk_bf16_f32 v2, v9, v7
	v_cvt_pk_bf16_f32 v3, v11, v13
	v_cvt_pk_bf16_f32 v4, v15, v17
	v_cvt_pk_bf16_f32 v5, v19, v21
	ds_read2_b32 v[8:9], v70 offset0:49 offset1:57
	ds_read2_b32 v[10:11], v70 offset0:16 offset1:24
	ds_read2_b32 v[12:13], v70 offset0:82 offset1:90
	ds_read2_b32 v[14:15], v70 offset0:115 offset1:123
	ds_read2_b32 v[16:17], v70 offset0:148 offset1:156
	ds_read2_b32 v[18:19], v70 offset0:181 offset1:189
	ds_read2_b32 v[20:21], v70 offset0:214 offset1:222
	ds_read2_b32 v[24:25], v70 offset0:247 offset1:255
	v_lshl_add_u64 v[6:7], v[22:23], 0, v[38:39]
	global_store_dwordx4 v[6:7], v[2:5], off sc1
	v_or_b32_e32 v6, s16, v67
	v_lshlrev_b32_e32 v38, 11, v6
	s_waitcnt lgkmcnt(6)
	v_cvt_pk_bf16_f32 v2, v10, v8
	s_waitcnt lgkmcnt(4)
	v_cvt_pk_bf16_f32 v3, v12, v14
	s_waitcnt lgkmcnt(2)
	v_cvt_pk_bf16_f32 v4, v16, v18
	s_waitcnt lgkmcnt(0)
	v_cvt_pk_bf16_f32 v5, v20, v24
	v_lshl_add_u64 v[6:7], v[22:23], 0, v[38:39]
	global_store_dwordx4 v[6:7], v[2:5], off sc1
	v_or_b32_e32 v6, s16, v69
	v_lshlrev_b32_e32 v38, 11, v6
	v_cvt_pk_bf16_f32 v2, v11, v9
	v_cvt_pk_bf16_f32 v3, v13, v15
	v_cvt_pk_bf16_f32 v4, v17, v19
	v_cvt_pk_bf16_f32 v5, v21, v25
	v_lshl_add_u64 v[6:7], v[22:23], 0, v[38:39]
	global_store_dwordx4 v[6:7], v[2:5], off sc1
	s_waitcnt lgkmcnt(0)

.LBB0_146:
	v_add_u32_e32 v11, 0x840, v19
	ds_write2_b32 v11, v6, v7 offset1:1
	v_add_u32_e32 v6, 0x848, v19
	ds_write2_b32 v6, v8, v9 offset1:1
	s_waitcnt vmcnt(0)
	v_pk_mul_f32 v[2:3], v[2:3], v[10:11] op_sel_hi:[1,0]
	v_add_u32_e32 v6, 0xc60, v19
	ds_write2_b32 v6, v2, v3 offset1:1
	v_pk_mul_f32 v[2:3], v[4:5], v[10:11] op_sel_hi:[1,0]
	v_add_u32_e32 v4, 0xc68, v19
	s_mul_i32 s1, s8, 0x150000
	ds_write2_b32 v4, v2, v3 offset1:1
	s_mul_hi_i32 s0, s8, 0x150000
	s_add_u32 s1, s86, s1
	s_waitcnt lgkmcnt(0)
	s_addc_u32 s10, s87, s0
	s_lshl_b32 s0, s89, 1
	s_add_u32 s0, s1, s0
	ds_read2_b32 v[6:7], v70 offset0:33 offset1:41
	ds_read2_b32 v[8:9], v70 offset1:8
	ds_read2_b32 v[10:11], v70 offset0:66 offset1:74
	ds_read2_b32 v[12:13], v70 offset0:99 offset1:107
	ds_read2_b32 v[14:15], v70 offset0:132 offset1:140
	ds_read2_b32 v[16:17], v70 offset0:165 offset1:173
	ds_read2_b32 v[18:19], v70 offset0:198 offset1:206
	ds_read2_b32 v[20:21], v70 offset0:231 offset1:239
	s_addc_u32 s1, s10, 0
	v_lshlrev_b32_e32 v38, 1, v42
	v_lshl_add_u64 v[2:3], s[0:1], 0, v[38:39]
	v_lshl_add_u64 v[22:23], v[2:3], 0, s[24:25]
	s_waitcnt lgkmcnt(6)
	v_cvt_pk_bf16_f32 v2, v8, v6
	v_or_b32_e32 v6, s16, v35
	v_mul_u32_u24_e32 v38, 0x300, v6
	s_waitcnt lgkmcnt(4)
	v_cvt_pk_bf16_f32 v3, v10, v12
	s_waitcnt lgkmcnt(2)
	v_cvt_pk_bf16_f32 v4, v14, v16
	s_waitcnt lgkmcnt(0)
	v_cvt_pk_bf16_f32 v5, v18, v20
	v_lshl_add_u64 v[24:25], v[22:23], 0, v[38:39]
	global_store_dwordx4 v[24:25], v[2:5], off sc1
	v_or_b32_e32 v6, s16, v59
	v_mul_u32_u24_e32 v38, 0x300, v6
	v_cvt_pk_bf16_f32 v2, v9, v7
	v_cvt_pk_bf16_f32 v3, v11, v13
	v_cvt_pk_bf16_f32 v4, v15, v17
	v_cvt_pk_bf16_f32 v5, v19, v21
	ds_read2_b32 v[8:9], v70 offset0:16 offset1:24
	ds_read2_b32 v[10:11], v70 offset0:49 offset1:57
	ds_read2_b32 v[12:13], v70 offset0:82 offset1:90
	ds_read2_b32 v[14:15], v70 offset0:115 offset1:123
	ds_read2_b32 v[16:17], v70 offset0:148 offset1:156
	ds_read2_b32 v[18:19], v70 offset0:181 offset1:189
	ds_read2_b32 v[20:21], v70 offset0:214 offset1:222
	ds_read2_b32 v[24:25], v70 offset0:247 offset1:255
	v_lshl_add_u64 v[6:7], v[22:23], 0, v[38:39]
	global_store_dwordx4 v[6:7], v[2:5], off sc1
	v_or_b32_e32 v6, s16, v67
	v_mul_u32_u24_e32 v38, 0x300, v6
	s_waitcnt lgkmcnt(6)
	v_cvt_pk_bf16_f32 v2, v8, v10
	s_waitcnt lgkmcnt(4)
	v_cvt_pk_bf16_f32 v3, v12, v14
	s_waitcnt lgkmcnt(2)
	v_cvt_pk_bf16_f32 v4, v16, v18
	s_waitcnt lgkmcnt(0)
	v_cvt_pk_bf16_f32 v5, v20, v24
	v_lshl_add_u64 v[6:7], v[22:23], 0, v[38:39]
	global_store_dwordx4 v[6:7], v[2:5], off sc1
	v_or_b32_e32 v6, s16, v69
	v_mul_u32_u24_e32 v38, 0x300, v6
	v_cvt_pk_bf16_f32 v2, v9, v11
	v_cvt_pk_bf16_f32 v3, v13, v15
	v_cvt_pk_bf16_f32 v4, v17, v19
	v_cvt_pk_bf16_f32 v5, v21, v25
	v_lshl_add_u64 v[6:7], v[22:23], 0, v[38:39]
	global_store_dwordx4 v[6:7], v[2:5], off sc1
	s_waitcnt lgkmcnt(0)

.LBB0_160:
	v_add_u32_e32 v11, 0x840, v19
	s_lshl_b32 s10, s90, 5
	s_mul_i32 s1, s8, 0x150000
	ds_write2_b32 v11, v6, v7 offset1:1
	v_add_u32_e32 v6, 0x848, v19
	s_mul_hi_i32 s0, s8, 0x150000
	s_add_u32 s1, s48, s1
	s_mulk_i32 s90, 0xab
	ds_write2_b32 v6, v8, v9 offset1:1
	s_waitcnt vmcnt(0)
	v_pk_mul_f32 v[2:3], v[2:3], v[10:11] op_sel_hi:[1,0]
	v_add_u32_e32 v6, 0xc60, v19
	s_addc_u32 s11, s49, s0
	s_bfe_u32 s0, s90, 0x6000a
	ds_write2_b32 v6, v2, v3 offset1:1
	v_pk_mul_f32 v[2:3], v[4:5], v[10:11] op_sel_hi:[1,0]
	v_add_u32_e32 v4, 0xc68, v19
	s_mul_i32 s0, s0, 6
	ds_write2_b32 v4, v2, v3 offset1:1
	s_sub_i32 s0, s89, s0
	s_waitcnt lgkmcnt(0)
	s_and_b32 s0, s0, 0xff
	s_cmp_gt_u32 s0, 3
	ds_read2_b32 v[6:7], v70 offset0:33 offset1:41
	ds_read2_b32 v[8:9], v70 offset1:8
	ds_read2_b32 v[10:11], v70 offset0:66 offset1:74
	ds_read2_b32 v[12:13], v70 offset0:99 offset1:107
	ds_read2_b32 v[14:15], v70 offset0:132 offset1:140
	ds_read2_b32 v[16:17], v70 offset0:165 offset1:173
	ds_read2_b32 v[18:19], v70 offset0:198 offset1:206
	ds_read2_b32 v[20:21], v70 offset0:231 offset1:239
	s_cselect_b64 vcc, -1, 0
	s_lshl_b32 s0, s16, 1
	s_add_u32 s0, s1, s0
	s_waitcnt lgkmcnt(6)
	v_cvt_pk_bf16_f32 v2, v8, v6
	v_cndmask_b32_e32 v6, v35, v72, vcc
	s_addc_u32 s1, s11, 0
	v_lshlrev_b32_e32 v38, 1, v42
	v_or_b32_e32 v6, s10, v6
	v_lshl_add_u64 v[22:23], s[0:1], 0, v[38:39]
	v_mul_u32_u24_e32 v38, 0x300, v6
	s_waitcnt lgkmcnt(4)
	v_cvt_pk_bf16_f32 v3, v10, v12
	s_waitcnt lgkmcnt(2)
	v_cvt_pk_bf16_f32 v4, v14, v16
	s_waitcnt lgkmcnt(0)
	v_cvt_pk_bf16_f32 v5, v18, v20
	v_lshl_add_u64 v[24:25], v[22:23], 0, v[38:39]
	v_cndmask_b32_e32 v6, v59, v73, vcc
	global_store_dwordx4 v[24:25], v[2:5], off sc1
	v_or_b32_e32 v6, s10, v6
	v_mul_u32_u24_e32 v38, 0x300, v6
	v_cvt_pk_bf16_f32 v2, v9, v7
	v_cvt_pk_bf16_f32 v3, v11, v13
	v_cvt_pk_bf16_f32 v4, v15, v17
	v_cvt_pk_bf16_f32 v5, v19, v21
	ds_read2_b32 v[8:9], v70 offset0:16 offset1:24
	ds_read2_b32 v[10:11], v70 offset0:49 offset1:57
	ds_read2_b32 v[12:13], v70 offset0:82 offset1:90
	ds_read2_b32 v[14:15], v70 offset0:115 offset1:123
	ds_read2_b32 v[16:17], v70 offset0:148 offset1:156
	ds_read2_b32 v[18:19], v70 offset0:181 offset1:189
	ds_read2_b32 v[20:21], v70 offset0:214 offset1:222
	ds_read2_b32 v[24:25], v70 offset0:247 offset1:255
	v_lshl_add_u64 v[6:7], v[22:23], 0, v[38:39]
	global_store_dwordx4 v[6:7], v[2:5], off sc1
	v_cndmask_b32_e32 v6, v67, v74, vcc
	v_or_b32_e32 v6, s10, v6
	v_mul_u32_u24_e32 v38, 0x300, v6
	s_waitcnt lgkmcnt(6)
	v_cvt_pk_bf16_f32 v2, v8, v10
	s_waitcnt lgkmcnt(4)
	v_cvt_pk_bf16_f32 v3, v12, v14
	s_waitcnt lgkmcnt(2)
	v_cvt_pk_bf16_f32 v4, v16, v18
	s_waitcnt lgkmcnt(0)
	v_cvt_pk_bf16_f32 v5, v20, v24
	v_lshl_add_u64 v[6:7], v[22:23], 0, v[38:39]
	global_store_dwordx4 v[6:7], v[2:5], off sc1
	v_cndmask_b32_e32 v6, v69, v75, vcc
	v_or_b32_e32 v6, s10, v6
	v_mul_u32_u24_e32 v38, 0x300, v6
	v_cvt_pk_bf16_f32 v2, v9, v11
	v_cvt_pk_bf16_f32 v3, v13, v15
	v_cvt_pk_bf16_f32 v4, v17, v19
	v_cvt_pk_bf16_f32 v5, v21, v25
	v_lshl_add_u64 v[6:7], v[22:23], 0, v[38:39]
	global_store_dwordx4 v[6:7], v[2:5], off sc1
	s_waitcnt lgkmcnt(0)

.LBB0_169:
	s_andn2_b64 vcc, exec, s[0:1]
	s_cbranch_vccnz .LBB0_171
	s_lshl_b32 s0, s88, 3
	s_and_b32 s0, s0, 0x1fc0
	s_add_i32 s16, s0, 0xffffe900
	s_lshl_b32 s0, s2, 5
	s_and_b32 s0, s0, 0xe0
	s_or_b32 s8, s0, 0x800
	s_lshl_b32 s0, s0, 2
	s_add_u32 s0, s6, s0
	v_or_b32_e32 v4, s16, v35
	s_addc_u32 s1, s7, 0
	v_mov_b32_e32 v63, v39
	v_lshl_add_u64 v[2:3], s[0:1], 0, v[62:63]
	v_mul_i32_i24_e32 v38, 0x1b00, v4
	v_lshl_add_u64 v[30:31], v[2:3], 0, v[38:39]
	v_add_co_u32_e32 v6, vcc, s75, v30
	v_add_u32_e32 v63, v43, v57
	s_nop 0
	v_addc_co_u32_e32 v7, vcc, 0, v31, vcc
	v_add_co_u32_e32 v10, vcc, s76, v30
	global_load_dwordx4 v[2:5], v[30:31], off offset:2816 nt
	s_nop 0
	global_load_dwordx4 v[6:9], v[6:7], off offset:768 nt
	v_addc_co_u32_e32 v11, vcc, 0, v31, vcc
	v_add_co_u32_e32 v14, vcc, s77, v30
	v_add_u32_e32 v64, 0x420, v63
	s_nop 0
	v_addc_co_u32_e32 v15, vcc, 0, v31, vcc
	v_add_co_u32_e32 v18, vcc, s78, v30
	global_load_dwordx4 v[10:13], v[10:11], off offset:2816 nt
	s_nop 0
	global_load_dwordx4 v[14:17], v[14:15], off offset:768 nt
	v_addc_co_u32_e32 v19, vcc, 0, v31, vcc
	v_add_co_u32_e32 v22, vcc, s79, v30
	v_add_u32_e32 v65, 0x428, v63
	s_nop 0
	v_addc_co_u32_e32 v23, vcc, 0, v31, vcc
	global_load_dwordx4 v[18:21], v[18:19], off offset:2816 nt
	s_nop 0
	global_load_dwordx4 v[22:25], v[22:23], off offset:768 nt
	v_add_co_u32_e32 v26, vcc, s80, v30
	v_add_u32_e32 v66, 0x840, v63
	s_nop 0
	v_addc_co_u32_e32 v27, vcc, 0, v31, vcc
	global_load_dwordx4 v[26:29], v[26:27], off offset:2816 nt
	v_add_co_u32_e32 v30, vcc, s81, v30
	v_add_u32_e32 v68, 0x848, v63
	s_nop 0
	v_addc_co_u32_e32 v31, vcc, 0, v31, vcc
	global_load_dwordx4 v[30:33], v[30:31], off offset:768 nt
	v_add_u32_e32 v82, 0xc60, v63
	v_add_u32_e32 v83, 0xc68, v63
	v_add_u32_e32 v84, 0x1080, v63
	v_add_u32_e32 v85, 0x1088, v63
	v_add_u32_e32 v86, 0x14a0, v63
	v_add_u32_e32 v87, 0x14a8, v63
	v_add_u32_e32 v88, 0x18c0, v63
	v_add_u32_e32 v89, 0x18c8, v63
	v_add_u32_e32 v90, 0x1ce0, v63
	v_add_u32_e32 v91, 0x1ce8, v63
	s_lshl_b64 s[0:1], s[16:17], 1
	s_add_u32 s0, s46, s0
	s_addc_u32 s1, s47, s1
	v_lshlrev_b32_e32 v38, 1, v42
	s_waitcnt vmcnt(7)
	ds_write2_b32 v63, v2, v3 offset1:1
	ds_write2_b32 v63, v4, v5 offset0:2 offset1:3
	s_waitcnt vmcnt(6)
	ds_write2_b32 v64, v6, v7 offset1:1
	ds_write2_b32 v65, v8, v9 offset1:1
	s_waitcnt vmcnt(5)
	ds_write2_b32 v66, v10, v11 offset1:1
	ds_write2_b32 v68, v12, v13 offset1:1
	s_waitcnt vmcnt(4)
	ds_write2_b32 v82, v14, v15 offset1:1
	ds_write2_b32 v83, v16, v17 offset1:1
	s_waitcnt vmcnt(3)
	ds_write2_b32 v84, v18, v19 offset1:1
	ds_write2_b32 v85, v20, v21 offset1:1
	s_waitcnt vmcnt(2)
	ds_write2_b32 v86, v22, v23 offset1:1
	ds_write2_b32 v87, v24, v25 offset1:1
	s_waitcnt vmcnt(1)
	ds_write2_b32 v88, v26, v27 offset1:1
	ds_write2_b32 v89, v28, v29 offset1:1
	s_waitcnt vmcnt(0)
	ds_write2_b32 v90, v30, v31 offset1:1
	ds_write2_b32 v91, v32, v33 offset1:1
	s_waitcnt lgkmcnt(0)
	ds_read2_b32 v[6:7], v70 offset0:33 offset1:41
	ds_read2_b32 v[8:9], v70 offset1:8
	ds_read2_b32 v[10:11], v70 offset0:66 offset1:74
	ds_read2_b32 v[12:13], v70 offset0:99 offset1:107
	ds_read2_b32 v[14:15], v70 offset0:132 offset1:140
	ds_read2_b32 v[16:17], v70 offset0:165 offset1:173
	ds_read2_b32 v[18:19], v70 offset0:198 offset1:206
	ds_read2_b32 v[20:21], v70 offset0:231 offset1:239
	s_waitcnt lgkmcnt(6)
	v_cvt_pk_bf16_f32 v2, v8, v6
	v_or_b32_e32 v6, s8, v35
	v_lshl_add_u64 v[22:23], s[0:1], 0, v[38:39]
	v_lshlrev_b32_e32 v38, 11, v6
	s_waitcnt lgkmcnt(4)
	v_cvt_pk_bf16_f32 v3, v10, v12
	s_waitcnt lgkmcnt(2)
	v_cvt_pk_bf16_f32 v4, v14, v16
	s_waitcnt lgkmcnt(0)
	v_cvt_pk_bf16_f32 v5, v18, v20
	v_lshl_add_u64 v[24:25], v[22:23], 0, v[38:39]
	global_store_dwordx4 v[24:25], v[2:5], off sc1
	v_or_b32_e32 v6, s8, v59
	v_lshlrev_b32_e32 v38, 11, v6
	v_cvt_pk_bf16_f32 v2, v9, v7
	v_cvt_pk_bf16_f32 v3, v11, v13
	v_cvt_pk_bf16_f32 v4, v15, v17
	v_cvt_pk_bf16_f32 v5, v19, v21
	ds_read2_b32 v[8:9], v70 offset0:49 offset1:57
	ds_read2_b32 v[10:11], v70 offset0:16 offset1:24
	ds_read2_b32 v[12:13], v70 offset0:82 offset1:90
	ds_read2_b32 v[14:15], v70 offset0:115 offset1:123
	ds_read2_b32 v[16:17], v70 offset0:148 offset1:156
	ds_read2_b32 v[18:19], v70 offset0:181 offset1:189
	ds_read2_b32 v[20:21], v70 offset0:214 offset1:222
	ds_read2_b32 v[24:25], v70 offset0:247 offset1:255
	v_lshl_add_u64 v[6:7], v[22:23], 0, v[38:39]
	global_store_dwordx4 v[6:7], v[2:5], off sc1
	v_or_b32_e32 v6, s8, v67
	v_lshlrev_b32_e32 v38, 11, v6
	s_waitcnt lgkmcnt(6)
	v_cvt_pk_bf16_f32 v2, v10, v8
	s_waitcnt lgkmcnt(4)
	v_cvt_pk_bf16_f32 v3, v12, v14
	s_waitcnt lgkmcnt(2)
	v_cvt_pk_bf16_f32 v4, v16, v18
	s_waitcnt lgkmcnt(0)
	v_cvt_pk_bf16_f32 v5, v20, v24
	v_lshl_add_u64 v[6:7], v[22:23], 0, v[38:39]
	global_store_dwordx4 v[6:7], v[2:5], off sc1
	v_or_b32_e32 v6, s8, v69
	v_lshlrev_b32_e32 v38, 11, v6
	v_cvt_pk_bf16_f32 v2, v11, v9
	v_cvt_pk_bf16_f32 v3, v13, v15
	v_cvt_pk_bf16_f32 v4, v17, v19
	v_cvt_pk_bf16_f32 v5, v21, v25
	v_lshl_add_u64 v[6:7], v[22:23], 0, v[38:39]
	global_store_dwordx4 v[6:7], v[2:5], off sc1
	s_waitcnt lgkmcnt(0)

.LBB0_172:
	s_andn2_b64 vcc, exec, s[0:1]
	s_cbranch_vccnz .LBB0_174
	s_add_i32 s0, s88, 0xfea0
	s_and_b32 s1, s0, 0xffff
	s_mul_i32 s1, s1, 0xaaab
	s_lshr_b32 s8, s1, 20
	s_mul_i32 s1, s8, 24
	s_sub_i32 s0, s0, s1
	s_lshl_b32 s1, s0, 5
	s_addk_i32 s1, 0x500
	s_lshl_b32 s0, s0, 7
	s_and_b32 s9, s1, 0xffe0
	s_and_b32 s0, s0, 0x3ff80
	s_add_u32 s0, s6, s0
	v_lshl_or_b32 v4, s8, 6, v35
	s_addc_u32 s1, s7, 0
	v_mov_b32_e32 v63, v39
	v_lshl_add_u64 v[2:3], s[0:1], 0, v[62:63]
	v_mul_u32_u24_e32 v38, 0x1b00, v4
	v_lshl_add_u64 v[30:31], v[2:3], 0, v[38:39]
	v_add_co_u32_e32 v6, vcc, s75, v30
	v_add_u32_e32 v63, v43, v57
	s_nop 0
	v_addc_co_u32_e32 v7, vcc, 0, v31, vcc
	v_add_co_u32_e32 v10, vcc, s76, v30
	global_load_dwordx4 v[2:5], v[30:31], off offset:3840 nt
	s_nop 0
	global_load_dwordx4 v[6:9], v[6:7], off offset:1792 nt
	v_addc_co_u32_e32 v11, vcc, 0, v31, vcc
	v_add_co_u32_e32 v14, vcc, s77, v30
	v_add_u32_e32 v64, 0x420, v63
	s_nop 0
	v_addc_co_u32_e32 v15, vcc, 0, v31, vcc
	v_add_co_u32_e32 v18, vcc, s78, v30
	global_load_dwordx4 v[10:13], v[10:11], off offset:3840 nt
	s_nop 0
	global_load_dwordx4 v[14:17], v[14:15], off offset:1792 nt
	v_addc_co_u32_e32 v19, vcc, 0, v31, vcc
	v_add_co_u32_e32 v22, vcc, s79, v30
	v_add_u32_e32 v65, 0x428, v63
	s_nop 0
	v_addc_co_u32_e32 v23, vcc, 0, v31, vcc
	global_load_dwordx4 v[18:21], v[18:19], off offset:3840 nt
	s_nop 0
	global_load_dwordx4 v[22:25], v[22:23], off offset:1792 nt
	v_add_co_u32_e32 v26, vcc, s80, v30
	v_add_u32_e32 v66, 0x840, v63
	s_nop 0
	v_addc_co_u32_e32 v27, vcc, 0, v31, vcc
	global_load_dwordx4 v[26:29], v[26:27], off offset:3840 nt
	v_add_co_u32_e32 v30, vcc, s81, v30
	v_add_u32_e32 v68, 0x848, v63
	s_nop 0
	v_addc_co_u32_e32 v31, vcc, 0, v31, vcc
	global_load_dwordx4 v[30:33], v[30:31], off offset:1792 nt
	v_add_u32_e32 v82, 0xc60, v63
	v_add_u32_e32 v83, 0xc68, v63
	v_add_u32_e32 v84, 0x1080, v63
	v_add_u32_e32 v85, 0x1088, v63
	v_add_u32_e32 v86, 0x14a0, v63
	v_add_u32_e32 v87, 0x14a8, v63
	v_add_u32_e32 v88, 0x18c0, v63
	v_add_u32_e32 v89, 0x18c8, v63
	v_add_u32_e32 v90, 0x1ce0, v63
	v_add_u32_e32 v91, 0x1ce8, v63
	s_lshl_b32 s0, s8, 7
	s_add_u32 s0, s46, s0
	s_addc_u32 s1, s47, 0
	v_lshlrev_b32_e32 v38, 1, v42
	s_waitcnt vmcnt(7)
	ds_write2_b32 v63, v2, v3 offset1:1
	ds_write2_b32 v63, v4, v5 offset0:2 offset1:3
	s_waitcnt vmcnt(6)
	ds_write2_b32 v64, v6, v7 offset1:1
	ds_write2_b32 v65, v8, v9 offset1:1
	s_waitcnt vmcnt(5)
	ds_write2_b32 v66, v10, v11 offset1:1
	ds_write2_b32 v68, v12, v13 offset1:1
	s_waitcnt vmcnt(4)
	ds_write2_b32 v82, v14, v15 offset1:1
	ds_write2_b32 v83, v16, v17 offset1:1
	s_waitcnt vmcnt(3)
	ds_write2_b32 v84, v18, v19 offset1:1
	ds_write2_b32 v85, v20, v21 offset1:1
	s_waitcnt vmcnt(2)
	ds_write2_b32 v86, v22, v23 offset1:1
	ds_write2_b32 v87, v24, v25 offset1:1
	s_waitcnt vmcnt(1)
	ds_write2_b32 v88, v26, v27 offset1:1
	ds_write2_b32 v89, v28, v29 offset1:1
	s_waitcnt vmcnt(0)
	ds_write2_b32 v90, v30, v31 offset1:1
	ds_write2_b32 v91, v32, v33 offset1:1
	s_waitcnt lgkmcnt(0)
	ds_read2_b32 v[6:7], v70 offset0:33 offset1:41
	ds_read2_b32 v[8:9], v70 offset1:8
	ds_read2_b32 v[10:11], v70 offset0:66 offset1:74
	ds_read2_b32 v[12:13], v70 offset0:99 offset1:107
	ds_read2_b32 v[14:15], v70 offset0:132 offset1:140
	ds_read2_b32 v[16:17], v70 offset0:165 offset1:173
	ds_read2_b32 v[18:19], v70 offset0:198 offset1:206
	ds_read2_b32 v[20:21], v70 offset0:231 offset1:239
	s_waitcnt lgkmcnt(6)
	v_cvt_pk_bf16_f32 v2, v8, v6
	v_or_b32_e32 v6, s9, v35
	v_lshl_add_u64 v[22:23], s[0:1], 0, v[38:39]
	v_lshlrev_b32_e32 v38, 11, v6
	s_waitcnt lgkmcnt(4)
	v_cvt_pk_bf16_f32 v3, v10, v12
	s_waitcnt lgkmcnt(2)
	v_cvt_pk_bf16_f32 v4, v14, v16
	s_waitcnt lgkmcnt(0)
	v_cvt_pk_bf16_f32 v5, v18, v20
	v_lshl_add_u64 v[24:25], v[22:23], 0, v[38:39]
	global_store_dwordx4 v[24:25], v[2:5], off sc1
	v_or_b32_e32 v6, s9, v59
	v_lshlrev_b32_e32 v38, 11, v6
	v_cvt_pk_bf16_f32 v2, v9, v7
	v_cvt_pk_bf16_f32 v3, v11, v13
	v_cvt_pk_bf16_f32 v4, v15, v17
	v_cvt_pk_bf16_f32 v5, v19, v21
	ds_read2_b32 v[8:9], v70 offset0:49 offset1:57
	ds_read2_b32 v[10:11], v70 offset0:16 offset1:24
	ds_read2_b32 v[12:13], v70 offset0:82 offset1:90
	ds_read2_b32 v[14:15], v70 offset0:115 offset1:123
	ds_read2_b32 v[16:17], v70 offset0:148 offset1:156
	ds_read2_b32 v[18:19], v70 offset0:181 offset1:189
	ds_read2_b32 v[20:21], v70 offset0:214 offset1:222
	ds_read2_b32 v[24:25], v70 offset0:247 offset1:255
	v_lshl_add_u64 v[6:7], v[22:23], 0, v[38:39]
	global_store_dwordx4 v[6:7], v[2:5], off sc1
	v_or_b32_e32 v6, s9, v67
	v_lshlrev_b32_e32 v38, 11, v6
	s_waitcnt lgkmcnt(6)
	v_cvt_pk_bf16_f32 v2, v10, v8
	s_waitcnt lgkmcnt(4)
	v_cvt_pk_bf16_f32 v3, v12, v14
	s_waitcnt lgkmcnt(2)
	v_cvt_pk_bf16_f32 v4, v16, v18
	s_waitcnt lgkmcnt(0)
	v_cvt_pk_bf16_f32 v5, v20, v24
	v_lshl_add_u64 v[6:7], v[22:23], 0, v[38:39]
	global_store_dwordx4 v[6:7], v[2:5], off sc1
	v_or_b32_e32 v6, s9, v69
	v_lshlrev_b32_e32 v38, 11, v6
	v_cvt_pk_bf16_f32 v2, v11, v9
	v_cvt_pk_bf16_f32 v3, v13, v15
	v_cvt_pk_bf16_f32 v4, v17, v19
	v_cvt_pk_bf16_f32 v5, v21, v25
	v_lshl_add_u64 v[6:7], v[22:23], 0, v[38:39]
	global_store_dwordx4 v[6:7], v[2:5], off sc1
	s_waitcnt lgkmcnt(0)

.LBB0_175:
	s_andn2_b64 vcc, exec, s[0:1]
	s_cbranch_vccnz .LBB0_177
	s_mul_hi_i32 s0, s88, 0x2e8ba2e9
	s_lshr_b32 s1, s0, 31
	s_ashr_i32 s0, s0, 2
	s_add_i32 s0, s0, s1
	s_mul_i32 s1, s0, 22
	s_sub_i32 s1, s88, s1
	s_lshl_b32 s8, s0, 6
	s_lshl_b32 s0, s1, 5
	s_ashr_i32 s1, s0, 31
	s_lshl_b64 s[10:11], s[0:1], 2
	s_add_u32 s6, s6, s10
	v_or_b32_e32 v32, s8, v35
	s_addc_u32 s7, s7, s11
	v_mov_b32_e32 v63, v39
	v_lshl_add_u64 v[30:31], s[6:7], 0, v[62:63]
	v_or_b32_e32 v4, 8, v32
	v_or_b32_e32 v10, 16, v32
	v_or_b32_e32 v12, 24, v32
	v_or_b32_e32 v18, 32, v32
	v_or_b32_e32 v20, 40, v32
	v_mad_i64_i32 v[2:3], s[6:7], v32, s74, v[30:31]
	v_mad_i64_i32 v[6:7], s[6:7], v4, s74, v[30:31]
	v_mad_i64_i32 v[10:11], s[6:7], v10, s74, v[30:31]
	v_mad_i64_i32 v[14:15], s[6:7], v12, s74, v[30:31]
	v_mad_i64_i32 v[18:19], s[6:7], v18, s74, v[30:31]
	v_mad_i64_i32 v[22:23], s[6:7], v20, s74, v[30:31]
	global_load_dwordx4 v[2:5], v[2:3], off nt
	s_nop 0
	global_load_dwordx4 v[6:9], v[6:7], off nt
	s_nop 0
	global_load_dwordx4 v[10:13], v[10:11], off nt
	s_nop 0
	global_load_dwordx4 v[14:17], v[14:15], off nt
	s_nop 0
	global_load_dwordx4 v[18:21], v[18:19], off nt
	s_nop 0
	global_load_dwordx4 v[22:25], v[22:23], off nt
	v_or_b32_e32 v26, 48, v32
	v_mad_i64_i32 v[26:27], s[6:7], v26, s74, v[30:31]
	global_load_dwordx4 v[26:29], v[26:27], off nt
	v_or_b32_e32 v32, 56, v32
	v_mad_i64_i32 v[30:31], s[6:7], v32, s74, v[30:31]
	global_load_dwordx4 v[30:33], v[30:31], off nt
	v_add_u32_e32 v63, v43, v57
	v_add_u32_e32 v66, 0x420, v63
	v_add_u32_e32 v68, 0x428, v63
	v_add_u32_e32 v84, 0x840, v63
	v_add_u32_e32 v85, 0x848, v63
	v_add_u32_e32 v86, 0xc60, v63
	v_add_u32_e32 v87, 0xc68, v63
	v_add_u32_e32 v88, 0x1080, v63
	v_add_u32_e32 v89, 0x1088, v63
	v_add_u32_e32 v90, 0x14a0, v63
	v_add_u32_e32 v91, 0x14a8, v63
	v_add_u32_e32 v92, 0x18c0, v63
	v_add_u32_e32 v93, 0x18c8, v63
	v_add_u32_e32 v94, 0x1ce0, v63
	v_add_u32_e32 v95, 0x1ce8, v63
	s_ashr_i32 s9, s8, 31
	s_lshl_b64 s[6:7], s[8:9], 1
	v_or_b32_e32 v64, s0, v35
	s_add_u32 s6, s46, s6
	v_lshlrev_b32_e32 v38, 1, v42
	v_ashrrev_i32_e32 v65, 31, v64
	s_addc_u32 s7, s47, s7
	v_lshlrev_b64 v[64:65], 11, v[64:65]
	v_lshl_add_u64 v[82:83], s[6:7], 0, v[38:39]
	s_waitcnt vmcnt(7)
	ds_write2_b32 v63, v2, v3 offset1:1
	ds_write2_b32 v63, v4, v5 offset0:2 offset1:3
	s_waitcnt vmcnt(6)
	ds_write2_b32 v66, v6, v7 offset1:1
	ds_write2_b32 v68, v8, v9 offset1:1
	s_waitcnt vmcnt(5)
	ds_write2_b32 v84, v10, v11 offset1:1
	ds_write2_b32 v85, v12, v13 offset1:1
	s_waitcnt vmcnt(4)
	ds_write2_b32 v86, v14, v15 offset1:1
	ds_write2_b32 v87, v16, v17 offset1:1
	s_waitcnt vmcnt(3)
	ds_write2_b32 v88, v18, v19 offset1:1
	ds_write2_b32 v89, v20, v21 offset1:1
	s_waitcnt vmcnt(2)
	ds_write2_b32 v90, v22, v23 offset1:1
	ds_write2_b32 v91, v24, v25 offset1:1
	s_waitcnt vmcnt(1)
	ds_write2_b32 v92, v26, v27 offset1:1
	ds_write2_b32 v93, v28, v29 offset1:1
	s_waitcnt vmcnt(0)
	ds_write2_b32 v94, v30, v31 offset1:1
	ds_write2_b32 v95, v32, v33 offset1:1
	s_waitcnt lgkmcnt(0)
	ds_read2_b32 v[6:7], v70 offset0:33 offset1:41
	ds_read2_b32 v[8:9], v70 offset1:8
	ds_read2_b32 v[10:11], v70 offset0:66 offset1:74
	ds_read2_b32 v[12:13], v70 offset0:99 offset1:107
	ds_read2_b32 v[14:15], v70 offset0:132 offset1:140
	ds_read2_b32 v[16:17], v70 offset0:165 offset1:173
	ds_read2_b32 v[18:19], v70 offset0:198 offset1:206
	ds_read2_b32 v[20:21], v70 offset0:231 offset1:239
	v_lshl_add_u64 v[22:23], v[82:83], 0, v[64:65]
	s_waitcnt lgkmcnt(6)
	v_cvt_pk_bf16_f32 v2, v8, v6
	s_waitcnt lgkmcnt(4)
	v_cvt_pk_bf16_f32 v3, v10, v12
	s_waitcnt lgkmcnt(2)
	v_cvt_pk_bf16_f32 v4, v14, v16
	s_waitcnt lgkmcnt(0)
	v_cvt_pk_bf16_f32 v5, v18, v20
	v_or_b32_e32 v6, s0, v59
	global_store_dwordx4 v[22:23], v[2:5], off sc1
	s_nop 1
	v_cvt_pk_bf16_f32 v2, v9, v7
	v_ashrrev_i32_e32 v7, 31, v6
	v_cvt_pk_bf16_f32 v3, v11, v13
	v_cvt_pk_bf16_f32 v4, v15, v17
	v_cvt_pk_bf16_f32 v5, v19, v21
	v_lshlrev_b64 v[6:7], 11, v[6:7]
	ds_read2_b32 v[8:9], v70 offset0:49 offset1:57
	ds_read2_b32 v[10:11], v70 offset0:16 offset1:24
	ds_read2_b32 v[12:13], v70 offset0:82 offset1:90
	ds_read2_b32 v[14:15], v70 offset0:115 offset1:123
	ds_read2_b32 v[16:17], v70 offset0:148 offset1:156
	ds_read2_b32 v[18:19], v70 offset0:181 offset1:189
	ds_read2_b32 v[20:21], v70 offset0:214 offset1:222
	ds_read2_b32 v[22:23], v70 offset0:247 offset1:255
	v_lshl_add_u64 v[6:7], v[82:83], 0, v[6:7]
	global_store_dwordx4 v[6:7], v[2:5], off sc1
	v_or_b32_e32 v6, s0, v67
	v_ashrrev_i32_e32 v7, 31, v6
	v_lshlrev_b64 v[6:7], 11, v[6:7]
	s_waitcnt lgkmcnt(6)
	v_cvt_pk_bf16_f32 v2, v10, v8
	s_waitcnt lgkmcnt(4)
	v_cvt_pk_bf16_f32 v3, v12, v14
	s_waitcnt lgkmcnt(2)
	v_cvt_pk_bf16_f32 v4, v16, v18
	s_waitcnt lgkmcnt(0)
	v_cvt_pk_bf16_f32 v5, v20, v22
	v_lshl_add_u64 v[6:7], v[82:83], 0, v[6:7]
	global_store_dwordx4 v[6:7], v[2:5], off sc1
	v_or_b32_e32 v6, s0, v69
	v_ashrrev_i32_e32 v7, 31, v6
	v_lshlrev_b64 v[6:7], 11, v[6:7]
	v_cvt_pk_bf16_f32 v2, v11, v9
	v_cvt_pk_bf16_f32 v3, v13, v15
	v_cvt_pk_bf16_f32 v4, v17, v19
	v_cvt_pk_bf16_f32 v5, v21, v23
	v_lshl_add_u64 v[6:7], v[82:83], 0, v[6:7]
	global_store_dwordx4 v[6:7], v[2:5], off sc1
	s_waitcnt lgkmcnt(0)
